# past: K/V staging loads issued before the item's first barrier (barrier only guards the LDS writes)
# baseline (speedup 1.0000x reference)
.LBB0_254:
	s_and_b32 s0, s34, 11
	s_cmp_lg_u32 s0, 0
	s_cselect_b64 s[16:17], -1, 0
	s_cmp_lg_u32 s0, 3
	s_cselect_b64 s[18:19], -1, 0
	s_and_b64 s[16:17], s[16:17], s[18:19]
	s_cmp_lg_u32 s34, 8
	s_cselect_b64 s[18:19], -1, 0
	s_and_b64 s[16:17], s[18:19], s[16:17]
	s_add_i32 s0, s34, -13
	s_cmp_lt_u32 s0, -2
	s_cselect_b64 s[18:19], -1, 0
	s_and_b64 s[16:17], s[18:19], s[16:17]
	s_waitcnt vmcnt(3)
	v_cndmask_b32_e64 v0, 0, 1, s[16:17]
	v_cmp_ne_u32_e32 vcc, v0, v177
	s_cbranch_vccnz .LBB0_253
	s_lshl_b32 s0, s34, 15
	v_lshl_add_u64 v[24:25], v[152:153], 0, s[0:1]
	s_lshl_b32 s0, s34, 9
	v_mov_b32_e32 v133, v117
	v_lshl_add_u64 v[28:29], v[154:155], 0, s[0:1]
	v_lshl_add_u64 v[0:1], v[24:25], 0, v[132:133]
	v_mov_b32_e32 v135, v117
	global_load_dwordx4 v[0:3], v[0:1], off
	s_waitcnt vmcnt(3)
	v_lshl_add_u64 v[4:5], v[28:29], 0, v[134:135]
	v_mov_b32_e32 v137, v117
	global_load_dwordx4 v[4:7], v[4:5], off
	s_waitcnt vmcnt(3)
	v_lshl_add_u64 v[8:9], v[24:25], 0, v[136:137]
	v_mov_b32_e32 v139, v117
	global_load_dwordx4 v[8:11], v[8:9], off
	s_waitcnt vmcnt(3)
	v_lshl_add_u64 v[12:13], v[28:29], 0, v[138:139]
	v_mov_b32_e32 v141, v117
	global_load_dwordx4 v[12:15], v[12:13], off
	v_lshl_add_u64 v[16:17], v[24:25], 0, v[140:141]
	v_mov_b32_e32 v143, v117
	global_load_dwordx4 v[16:19], v[16:17], off
	v_lshl_add_u64 v[20:21], v[28:29], 0, v[142:143]
	v_mov_b32_e32 v149, v117
	global_load_dwordx4 v[20:23], v[20:21], off
	v_lshl_add_u64 v[24:25], v[24:25], 0, v[148:149]
	v_mov_b32_e32 v151, v117
	global_load_dwordx4 v[24:27], v[24:25], off
	v_lshl_add_u64 v[28:29], v[28:29], 0, v[150:151]
	global_load_dwordx4 v[28:31], v[28:29], off
	s_add_i32 s18, s34, s33
	s_ashr_i32 s19, s18, 31
	s_lshl_b64 s[16:17], s[18:19], 2
	s_add_u32 s16, s46, s16
	s_addc_u32 s17, s47, s17
	s_lshl_b64 s[18:19], s[18:19], 13
	s_add_u32 s18, s48, s18
	s_addc_u32 s19, s49, s19
	v_lshlrev_b32_e32 v232, 1, v175
	v_lshlrev_b32_e32 v233, 1, v176
	global_load_ushort v230, v232, s[18:19]
	global_load_ushort v231, v233, s[18:19]
	s_barrier
	s_waitcnt vmcnt(9)
	ds_write_b128 v115, v[0:3]
	s_waitcnt vmcnt(8)
	ds_write_b128 v168, v[4:7]
	s_waitcnt vmcnt(7)
	ds_write_b128 v169, v[8:11]
	s_waitcnt vmcnt(6)
	ds_write_b128 v170, v[12:15]
	s_waitcnt vmcnt(5)
	ds_write_b128 v171, v[16:19]
	s_waitcnt vmcnt(4)
	ds_write_b128 v172, v[20:23]
	s_waitcnt vmcnt(3)
	ds_write_b128 v173, v[24:27]
	s_waitcnt vmcnt(2)
	ds_write_b128 v174, v[28:31]
	s_waitcnt lgkmcnt(0)
	s_waitcnt vmcnt(1)
	v_and_b32_e32 v137, 0xfff, v230
	v_lshlrev_b32_e32 v232, 7, v137
	v_mov_b32_e32 v233, 0
	v_lshl_add_u64 v[4:5], v[156:157], 0, v[232:233]
	global_load_dwordx4 v[0:3], v[4:5], off
	s_nop 0
	global_load_dwordx4 v[4:7], v[4:5], off offset:64
	s_waitcnt vmcnt(2)
	v_and_b32_e32 v139, 0xfff, v231
	v_lshlrev_b32_e32 v232, 7, v139
	v_lshl_add_u64 v[12:13], v[156:157], 0, v[232:233]
	global_load_dwordx4 v[8:11], v[12:13], off
	s_nop 0
	global_load_dwordx4 v[12:15], v[12:13], off offset:64
	s_barrier
	global_load_dword v133, v117, s[16:17]
	s_waitcnt vmcnt(0)
	v_add_u32_e32 v232, 31, v133
	v_ashrrev_i32_e32 v135, 5, v232
	v_cmp_lt_i32_e32 vcc, v196, v135
	s_and_saveexec_b64 s[16:17], vcc
	s_cbranch_execz .LBB0_252
	v_cmp_lt_i32_e64 s[20:21], v175, v133
	v_cmp_lt_i32_e64 s[24:25], v176, v133
	s_mov_b64 s[22:23], 0
	v_mov_b32_e32 v143, v196
	v_mov_b32_e32 v141, v230
	v_mov_b32_e32 v149, v231
	s_branch .LBB0_258
